# attention: hand-scheduled two-tile stage body (QK of tile b under softmax of tile a, PV of a under max+softmax of b), conflict-free V LDS layout, staging moved into PV(b), prio 1 for waves 4-7
# speedup vs baseline: 1.0751x; 1.0221x over previous
.LBB0_109:
	v_mov_b32_e32 v4, v216
	s_lshl_b32 s2, s6, 6
	v_readfirstlane_b32 s9, v4
	s_bfe_u32 s8, s9, 0x20006
	s_and_b32 s12, s2, 0xffffe000
	s_lshl_b32 s2, s10, 7
	s_lshl_b32 s3, s8, 5
	s_add_i32 s2, s2, s12
	v_and_b32_e32 v6, 31, v4
	s_or_b32 s7, s2, s3
	v_or_b32_e32 v2, s7, v6
	v_ashrrev_i32_e32 v3, 31, v2
	v_readlane_b32 s2, v254, 4
	v_lshlrev_b64 v[2:3], 11, v[2:3]
	v_readlane_b32 s3, v254, 5
	s_ashr_i32 s11, s9, 8
	v_bfe_u32 v5, v4, 5, 1
	v_lshl_add_u64 v[2:3], s[2:3], 0, v[2:3]
	s_lshl_b32 s2, s6, 3
	s_and_b32 s13, s2, 0x380
	s_lshl_b32 s90, s13, 1
	s_lshl_b32 s2, s11, 6
	v_lshl_add_u64 v[2:3], v[2:3], 0, s[90:91]
	s_ashr_i32 s3, s2, 31
	v_lshl_add_u64 v[2:3], s[2:3], 1, v[2:3]
	v_lshlrev_b32_e32 v0, 4, v5
	v_lshl_add_u64 v[8:9], v[2:3], 0, v[0:1]
	v_ashrrev_i32_e32 v0, 4, v4
	v_and_b32_e32 v7, 15, v4
	v_add_u32_e32 v2, s12, v0
	v_lshlrev_b32_e32 v168, 3, v7
	v_ashrrev_i32_e32 v3, 31, v2
	v_or_b32_e32 v173, s13, v168
	v_lshlrev_b64 v[10:11], 11, v[2:3]
	v_lshl_or_b32 v10, v173, 1, v10
	v_lshl_add_u64 v[12:13], s[86:87], 0, v[10:11]
	global_load_dwordx4 v[112:115], v[8:9], off
	global_load_dwordx4 v[116:119], v[8:9], off offset:32
	v_lshl_add_u64 v[14:15], s[88:89], 0, v[10:11]
	global_load_dwordx4 v[128:131], v[12:13], off
	global_load_dwordx4 v[132:135], v[14:15], off
	v_lshl_add_u64 v[12:13], v[10:11], 0, s[14:15]
	v_lshl_add_u64 v[14:15], s[86:87], 0, v[12:13]
	v_lshl_add_u64 v[12:13], s[88:89], 0, v[12:13]
	global_load_dwordx4 v[136:139], v[14:15], off
	global_load_dwordx4 v[140:143], v[12:13], off
	v_lshl_add_u64 v[12:13], v[10:11], 0, s[24:25]
	v_lshl_add_u64 v[14:15], s[86:87], 0, v[12:13]
	v_lshl_add_u64 v[12:13], s[88:89], 0, v[12:13]
	global_load_dwordx4 v[144:147], v[14:15], off
	global_load_dwordx4 v[148:151], v[12:13], off
	v_lshl_add_u64 v[10:11], v[10:11], 0, s[30:31]
	v_lshl_add_u64 v[12:13], s[86:87], 0, v[10:11]
	v_lshl_add_u64 v[10:11], s[88:89], 0, v[10:11]
	global_load_dwordx4 v[152:155], v[12:13], off
	global_load_dwordx4 v[156:159], v[10:11], off
	global_load_dwordx4 v[120:123], v[8:9], off offset:64
	global_load_dwordx4 v[124:127], v[8:9], off offset:96
	v_lshlrev_b32_e32 v169, 4, v7
	s_movk_i32 s3, 0x100
	v_mul_lo_u32 v174, v0, s26
	v_mul_lo_u32 v175, v0, s3
	v_add_u32_e32 v176, 0, v169
	v_and_b32_e32 v3, 3, v0
	v_lshlrev_b32_e32 v3, 2, v3
	v_xor_b32_e32 v3, v3, v7
	v_lshl_add_u32 v177, v3, 4, s16
	v_add_u32_e32 v3, v176, v174
	v_add_u32_e32 v7, v177, v175
	s_cmp_eq_u32 s10, 0
	s_waitcnt vmcnt(9)
	ds_write_b128 v3, v[128:131]
	s_waitcnt vmcnt(8)
	ds_write_b128 v7, v[132:135]
	s_waitcnt vmcnt(7)
	ds_write_b128 v3, v[136:139] offset:8704
	s_waitcnt vmcnt(6)
	ds_write_b128 v7, v[140:143] offset:8192
	s_waitcnt vmcnt(5)
	ds_write_b128 v3, v[144:147] offset:17408
	s_waitcnt vmcnt(4)
	ds_write_b128 v7, v[148:151] offset:16384
	s_waitcnt vmcnt(3)
	ds_write_b128 v3, v[152:155] offset:26112
	s_waitcnt vmcnt(2)
	ds_write_b128 v7, v[156:159] offset:24576
	s_cbranch_scc1 .LBB0_111
	v_add_u32_e32 v2, 0x80, v2
	v_ashrrev_i32_e32 v3, 31, v2
	v_lshlrev_b64 v[2:3], 11, v[2:3]
	v_lshl_or_b32 v2, v173, 1, v2
	v_lshl_add_u64 v[8:9], s[86:87], 0, v[2:3]
	v_lshl_add_u64 v[10:11], s[88:89], 0, v[2:3]
	global_load_dwordx4 v[128:131], v[8:9], off
	global_load_dwordx4 v[132:135], v[10:11], off
	v_lshl_add_u64 v[8:9], v[2:3], 0, s[14:15]
	v_lshl_add_u64 v[10:11], s[86:87], 0, v[8:9]
	v_lshl_add_u64 v[8:9], s[88:89], 0, v[8:9]
	global_load_dwordx4 v[136:139], v[10:11], off
	global_load_dwordx4 v[140:143], v[8:9], off
	v_lshl_add_u64 v[8:9], v[2:3], 0, s[24:25]
	v_lshl_add_u64 v[10:11], s[86:87], 0, v[8:9]
	v_lshl_add_u64 v[8:9], s[88:89], 0, v[8:9]
	v_lshl_add_u64 v[2:3], v[2:3], 0, s[30:31]
	global_load_dwordx4 v[144:147], v[10:11], off
	global_load_dwordx4 v[148:151], v[8:9], off
	v_lshl_add_u64 v[8:9], s[86:87], 0, v[2:3]
	v_lshl_add_u64 v[2:3], s[88:89], 0, v[2:3]
	global_load_dwordx4 v[152:155], v[8:9], off
	global_load_dwordx4 v[156:159], v[2:3], off
.LBB0_111:
	v_and_b32_e32 v170, 63, v4
	v_lshlrev_b32_e32 v2, 3, v5
	s_and_b32 s12, s5, 0xffffe000
	v_lshlrev_b32_e32 v172, 2, v5
	v_lshrrev_b32_e32 v3, 2, v4
	v_lshlrev_b32_e32 v5, 1, v4
	v_lshlrev_b32_e32 v4, 3, v4
	v_or_b32_e32 v2, s2, v2
	v_and_or_b32 v3, v3, 3, v172
	v_and_b32_e32 v5, 32, v5
	v_and_b32_e32 v4, 24, v4
	v_add_u32_e32 v0, s12, v0
	v_mov_b32_e32 v14, v1
	v_mov_b32_e32 v15, v1
	s_lshl_b32 s3, s10, 1
	s_lshr_b32 s13, s8, 1
	v_mul_u32_u24_e32 v171, 0x110, v6
	v_mad_u32_u24 v178, v6, s26, 0
	v_add3_u32 v179, s16, v5, v4
	v_lshlrev_b32_e32 v180, 1, v2
	v_mul_u32_u24_e32 v181, 0x100, v3
	v_add_u32_e32 v179, v179, v181
	v_and_b32_e32 v181, 3, v3
	v_lshl_add_u32 v179, v181, 6, v179
	v_add_u32_e32 v164, 0x160, v0
	v_mov_b32_e32 v0, v1
	v_mov_b32_e32 v2, v1
	v_mov_b32_e32 v3, v1
	v_mov_b32_e32 v4, v1
	v_mov_b32_e32 v5, v1
	v_mov_b32_e32 v6, v1
	v_mov_b32_e32 v7, v1
	v_mov_b32_e32 v8, v1
	v_mov_b32_e32 v9, v1
	v_mov_b32_e32 v10, v1
	v_mov_b32_e32 v11, v1
	v_mov_b32_e32 v12, v1
	v_mov_b32_e32 v13, v1
	v_mov_b64_e32 v[30:31], v[14:15]
	v_mov_b64_e32 v[46:47], v[14:15]
	v_mov_b64_e32 v[62:63], v[14:15]
	v_mov_b64_e32 v[78:79], v[14:15]
	s_or_b32 s3, s13, s3
	s_mov_b32 s2, 0
	v_mov_b32_e32 v183, 0xf149f2ca
	v_mov_b32_e32 v182, 0
	v_mov_b64_e32 v[28:29], v[12:13]
	v_mov_b64_e32 v[26:27], v[10:11]
	v_mov_b64_e32 v[24:25], v[8:9]
	v_mov_b64_e32 v[22:23], v[6:7]
	v_mov_b64_e32 v[20:21], v[4:5]
	v_mov_b64_e32 v[18:19], v[2:3]
	v_mov_b64_e32 v[16:17], v[0:1]
	v_mov_b64_e32 v[44:45], v[12:13]
	v_mov_b64_e32 v[42:43], v[10:11]
	v_mov_b64_e32 v[40:41], v[8:9]
	v_mov_b64_e32 v[38:39], v[6:7]
	v_mov_b64_e32 v[36:37], v[4:5]
	v_mov_b64_e32 v[34:35], v[2:3]
	v_mov_b64_e32 v[32:33], v[0:1]
	v_mov_b64_e32 v[60:61], v[12:13]
	v_mov_b64_e32 v[58:59], v[10:11]
	v_mov_b64_e32 v[56:57], v[8:9]
	v_mov_b64_e32 v[54:55], v[6:7]
	v_mov_b64_e32 v[52:53], v[4:5]
	v_mov_b64_e32 v[50:51], v[2:3]
	v_mov_b64_e32 v[48:49], v[0:1]
	v_mov_b64_e32 v[76:77], v[12:13]
	v_mov_b64_e32 v[74:75], v[10:11]
	v_mov_b64_e32 v[72:73], v[8:9]
	v_mov_b64_e32 v[70:71], v[6:7]
	v_mov_b64_e32 v[68:69], v[4:5]
	v_mov_b64_e32 v[66:67], v[2:3]
	v_mov_b64_e32 v[64:65], v[0:1]
	s_cmp_eq_u32 s11, 1
	s_cbranch_scc0 .Lattn_prio_skip
	s_setprio 1
.Lattn_prio_skip:
	s_mov_b32 s12, 0
	s_waitcnt lgkmcnt(0)
	s_barrier
	s_add_i32 s13, s12, 1
	s_branch .LBB0_116

.LBB0_116:
	s_and_b32 s14, s12, 1
	s_mul_i32 s15, s14, 0x8800
	s_mul_i32 s14, s14, 0x9000
	v_add_u32_e32 v2, s15, v178
	v_add_u32_e32 v0, s14, v179
	s_cmp_gt_u32 s2, s3
	v_add_u32_e32 v6, v2, v180
	v_xor_b32_e32 v198, 64, v0
	v_xor_b32_e32 v199, 0x80, v0
	v_xor_b32_e32 v200, 0xc0, v0
	s_cmp_lt_u32 s2, s3
	s_cbranch_scc1 .Lattn_pair
	s_cmp_gt_u32 s2, s3
	s_cbranch_scc1 .LBB0_121
	ds_read_b128 v[2:5], v6
	s_waitcnt lgkmcnt(0)
	v_mfma_f32_32x32x16_bf16 v[96:111], v[2:5], v[112:115], 0
	ds_read_b128 v[2:5], v6 offset:8704
	s_waitcnt lgkmcnt(0)
	v_mfma_f32_32x32x16_bf16 v[80:95], v[2:5], v[112:115], 0
	ds_read_b128 v[2:5], v6 offset:32
	s_waitcnt lgkmcnt(0)
	v_mfma_f32_32x32x16_bf16 v[96:111], v[2:5], v[116:119], v[96:111]
	ds_read_b128 v[2:5], v6 offset:8736
	s_waitcnt lgkmcnt(0)
	v_mfma_f32_32x32x16_bf16 v[80:95], v[2:5], v[116:119], v[80:95]
	ds_read_b128 v[2:5], v6 offset:64
	s_waitcnt vmcnt(1) lgkmcnt(0)
	v_mfma_f32_32x32x16_bf16 v[96:111], v[2:5], v[120:123], v[96:111]
	ds_read_b128 v[2:5], v6 offset:8768
	s_waitcnt lgkmcnt(0)
	v_mfma_f32_32x32x16_bf16 v[80:95], v[2:5], v[120:123], v[80:95]
	ds_read_b128 v[2:5], v6 offset:8800
	s_waitcnt vmcnt(0) lgkmcnt(0)
	v_mfma_f32_32x32x16_bf16 v[80:95], v[2:5], v[124:127], v[80:95]
	ds_read_b128 v[2:5], v6 offset:96
	s_waitcnt lgkmcnt(0)
	v_mfma_f32_32x32x16_bf16 v[96:111], v[2:5], v[124:127], v[96:111]
	s_nop 8
	v_max3_f32 v2, v80, v81, v82
	v_max3_f32 v3, v83, v84, v85
	v_max3_f32 v4, v86, v87, v88
	v_max3_f32 v5, v89, v90, v91
	v_max3_f32 v2, v2, v92, v93
	v_max3_f32 v3, v3, v94, v95
	v_max3_f32 v4, v4, v96, v97
	v_max3_f32 v5, v5, v98, v99
	v_max3_f32 v2, v2, v100, v101
	v_max3_f32 v3, v3, v102, v103
	v_max3_f32 v4, v4, v104, v105
	v_max3_f32 v5, v5, v106, v107
	v_max3_f32 v2, v2, v108, v109
	v_max3_f32 v3, v3, v110, v111
	v_max3_f32 v2, v2, v3, v4
	v_max_f32_e32 v2, v2, v5
	v_and_b32_e32 v4, 64, v220
	v_xor_b32_e32 v3, 32, v220
	v_add_u32_e32 v4, 64, v4
	v_cmp_lt_i32_e32 vcc, v3, v4
	s_nop 1
	v_cndmask_b32_e32 v3, v220, v3, vcc
	v_lshlrev_b32_e32 v3, 2, v3
	ds_bpermute_b32 v3, v3, v2
	s_waitcnt lgkmcnt(0)
	v_max3_f32 v7, v183, v2, v3
	v_cmp_gt_f32_e32 vcc, v7, v183
	s_cbranch_vccz .LBB0_119
	v_sub_f32_e32 v2, v183, v7
	v_mul_f32_e32 v2, 0x3e38aa3b, v2
	v_exp_f32_e32 v2, v2
	s_nop 0
	v_pk_mul_f32 v[78:79], v[78:79], v[2:3] op_sel_hi:[1,0]
	v_pk_mul_f32 v[76:77], v[76:77], v[2:3] op_sel_hi:[1,0]
	v_pk_mul_f32 v[74:75], v[74:75], v[2:3] op_sel_hi:[1,0]
	v_pk_mul_f32 v[72:73], v[72:73], v[2:3] op_sel_hi:[1,0]
	v_pk_mul_f32 v[70:71], v[70:71], v[2:3] op_sel_hi:[1,0]
	v_pk_mul_f32 v[68:69], v[68:69], v[2:3] op_sel_hi:[1,0]
	v_pk_mul_f32 v[66:67], v[66:67], v[2:3] op_sel_hi:[1,0]
	v_pk_mul_f32 v[64:65], v[64:65], v[2:3] op_sel_hi:[1,0]
	v_pk_mul_f32 v[62:63], v[62:63], v[2:3] op_sel_hi:[1,0]
	v_pk_mul_f32 v[60:61], v[60:61], v[2:3] op_sel_hi:[1,0]
	v_pk_mul_f32 v[58:59], v[58:59], v[2:3] op_sel_hi:[1,0]
	v_pk_mul_f32 v[56:57], v[56:57], v[2:3] op_sel_hi:[1,0]
	v_pk_mul_f32 v[54:55], v[54:55], v[2:3] op_sel_hi:[1,0]
	v_pk_mul_f32 v[52:53], v[52:53], v[2:3] op_sel_hi:[1,0]
	v_pk_mul_f32 v[50:51], v[50:51], v[2:3] op_sel_hi:[1,0]
	v_pk_mul_f32 v[48:49], v[48:49], v[2:3] op_sel_hi:[1,0]
	v_pk_mul_f32 v[46:47], v[46:47], v[2:3] op_sel_hi:[1,0]
	v_pk_mul_f32 v[44:45], v[44:45], v[2:3] op_sel_hi:[1,0]
	v_pk_mul_f32 v[42:43], v[42:43], v[2:3] op_sel_hi:[1,0]
	v_pk_mul_f32 v[40:41], v[40:41], v[2:3] op_sel_hi:[1,0]
	v_pk_mul_f32 v[38:39], v[38:39], v[2:3] op_sel_hi:[1,0]
	v_pk_mul_f32 v[36:37], v[36:37], v[2:3] op_sel_hi:[1,0]
	v_pk_mul_f32 v[34:35], v[34:35], v[2:3] op_sel_hi:[1,0]
	v_pk_mul_f32 v[32:33], v[32:33], v[2:3] op_sel_hi:[1,0]
	v_pk_mul_f32 v[30:31], v[30:31], v[2:3] op_sel_hi:[1,0]
	v_pk_mul_f32 v[28:29], v[28:29], v[2:3] op_sel_hi:[1,0]
	v_pk_mul_f32 v[26:27], v[26:27], v[2:3] op_sel_hi:[1,0]
	v_pk_mul_f32 v[24:25], v[24:25], v[2:3] op_sel_hi:[1,0]
	v_pk_mul_f32 v[22:23], v[22:23], v[2:3] op_sel_hi:[1,0]
	v_pk_mul_f32 v[20:21], v[20:21], v[2:3] op_sel_hi:[1,0]
	v_pk_mul_f32 v[18:19], v[18:19], v[2:3] op_sel_hi:[1,0]
	v_pk_mul_f32 v[16:17], v[16:17], v[2:3] op_sel_hi:[1,0]
	v_mul_f32_e32 v182, v182, v2
.LBB0_119:
	v_mul_f32_e32 v165, 0xbe38aa3b, v7
	v_fmamk_f32 v2, v96, 0x3e38aa3b, v165
	v_exp_f32_e32 v8, v2
	v_fmamk_f32 v2, v80, 0x3e38aa3b, v165
	v_exp_f32_e32 v183, v2
	v_fmamk_f32 v2, v97, 0x3e38aa3b, v165
	v_exp_f32_e32 v188, v2
	v_fmamk_f32 v2, v81, 0x3e38aa3b, v165
	v_exp_f32_e32 v191, v2
	v_fmamk_f32 v2, v98, 0x3e38aa3b, v165
	v_exp_f32_e32 v189, v2
	v_fmamk_f32 v2, v82, 0x3e38aa3b, v165
	v_exp_f32_e32 v192, v2
	v_fmamk_f32 v2, v99, 0x3e38aa3b, v165
	v_exp_f32_e32 v193, v2
	v_fmamk_f32 v2, v83, 0x3e38aa3b, v165
	v_exp_f32_e32 v194, v2
	v_fmamk_f32 v2, v100, 0x3e38aa3b, v165
	v_exp_f32_e32 v185, v2
	v_fmamk_f32 v2, v84, 0x3e38aa3b, v165
	v_exp_f32_e32 v187, v2
	v_fmamk_f32 v2, v101, 0x3e38aa3b, v165
	v_exp_f32_e32 v184, v2
	v_fmamk_f32 v2, v102, 0x3e38aa3b, v165
	v_exp_f32_e32 v3, v2
	v_fmamk_f32 v2, v103, 0x3e38aa3b, v165
	v_exp_f32_e32 v2, v2
	v_mov_b32_e32 v195, v0
	ds_read_b64_tr_b16 v[12:13], v0
	ds_read_b64_tr_b16 v[14:15], v0 offset:2048
	v_pk_mov_b32 v[10:11], v[184:185], v[184:185] op_sel:[1,0]
	v_pk_mov_b32 v[80:81], v[2:3], v[2:3] op_sel:[1,0]
	v_add_f32_e32 v190, v183, v8
	v_cvt_pk_bf16_f32 v8, v8, v188
	v_cvt_pk_bf16_f32 v9, v189, v193
	v_cvt_pk_bf16_f32 v10, v10, v11
	v_cvt_pk_bf16_f32 v11, v80, v81
	v_fmamk_f32 v4, v104, 0x3e38aa3b, v165
	v_exp_f32_e32 v5, v4
	s_waitcnt lgkmcnt(0)
	v_mfma_f32_32x32x16_bf16 v[64:79], v[12:15], v[8:11], v[64:79]
	v_fmamk_f32 v12, v106, 0x3e38aa3b, v165
	v_fmamk_f32 v4, v105, 0x3e38aa3b, v165
	v_exp_f32_e32 v105, v12
	v_fmamk_f32 v12, v107, 0x3e38aa3b, v165
	v_exp_f32_e32 v104, v12
	v_fmamk_f32 v12, v108, 0x3e38aa3b, v165
	v_exp_f32_e32 v107, v12
	v_fmamk_f32 v12, v109, 0x3e38aa3b, v165
	ds_read_b64_tr_b16 v[80:81], v198
	ds_read_b64_tr_b16 v[96:97], v199
	ds_read_b64_tr_b16 v[100:101], v200
	ds_read_b64_tr_b16 v[82:83], v198 offset:2048
	ds_read_b64_tr_b16 v[98:99], v199 offset:2048
	ds_read_b64_tr_b16 v[102:103], v200 offset:2048
	v_exp_f32_e32 v106, v12
	v_fmamk_f32 v12, v110, 0x3e38aa3b, v165
	v_exp_f32_e32 v4, v4
	v_exp_f32_e32 v109, v12
	v_fmamk_f32 v12, v111, 0x3e38aa3b, v165
	v_exp_f32_e32 v108, v12
	s_waitcnt lgkmcnt(2)
	v_mfma_f32_32x32x16_bf16 v[48:63], v[80:83], v[8:11], v[48:63]
	ds_read_b64_tr_b16 v[80:81], v0 offset:4096
	ds_read_b64_tr_b16 v[82:83], v0 offset:6144
	v_pk_mov_b32 v[12:13], v[4:5], v[4:5] op_sel:[1,0]
	v_pk_mov_b32 v[14:15], v[104:105], v[104:105] op_sel:[1,0]
	v_cvt_pk_bf16_f32 v12, v12, v13
	v_cvt_pk_bf16_f32 v13, v14, v15
	v_pk_mov_b32 v[14:15], v[106:107], v[106:107] op_sel:[1,0]
	v_add_f32_e32 v197, v192, v189
	s_waitcnt lgkmcnt(3)
	v_mfma_f32_32x32x16_bf16 v[32:47], v[96:99], v[8:11], v[32:47]
	v_pk_mov_b32 v[96:97], v[108:109], v[108:109] op_sel:[1,0]
	v_cvt_pk_bf16_f32 v14, v14, v15
	v_cvt_pk_bf16_f32 v15, v96, v97
	v_add_f32_e32 v196, v191, v188
	v_add_f32_e32 v193, v194, v193
	s_waitcnt lgkmcnt(0)
	v_mfma_f32_32x32x16_bf16 v[64:79], v[80:83], v[12:15], v[64:79]
	v_fmamk_f32 v80, v85, 0x3e38aa3b, v165
	v_exp_f32_e32 v186, v80
	v_fmamk_f32 v80, v86, 0x3e38aa3b, v165
	v_pk_add_f32 v[110:111], v[186:187], v[184:185]
	v_exp_f32_e32 v185, v80
	v_mfma_f32_32x32x16_bf16 v[16:31], v[100:103], v[8:11], v[16:31]
	ds_read_b64_tr_b16 v[8:9], v198 offset:4096
	ds_read_b64_tr_b16 v[96:97], v199 offset:4096
	ds_read_b64_tr_b16 v[100:101], v200 offset:4096
	ds_read_b64_tr_b16 v[10:11], v198 offset:6144
	ds_read_b64_tr_b16 v[98:99], v199 offset:6144
	ds_read_b64_tr_b16 v[102:103], v200 offset:6144
	ds_read_b64_tr_b16 v[80:81], v0 offset:8192
	ds_read_b64_tr_b16 v[82:83], v0 offset:10240
	s_waitcnt lgkmcnt(4)
	v_mfma_f32_32x32x16_bf16 v[48:63], v[8:11], v[12:15], v[48:63]
	v_fmamk_f32 v8, v87, 0x3e38aa3b, v165
	v_exp_f32_e32 v184, v8
	v_fmamk_f32 v8, v88, 0x3e38aa3b, v165
	v_exp_f32_e32 v189, v8
	v_fmamk_f32 v8, v89, 0x3e38aa3b, v165
	v_pk_mov_b32 v[10:11], v[186:187], v[186:187] op_sel:[1,0]
	v_pk_mov_b32 v[84:85], v[184:185], v[184:185] op_sel:[1,0]
	v_exp_f32_e32 v188, v8
	v_cvt_pk_bf16_f32 v8, v183, v191
	v_cvt_pk_bf16_f32 v9, v192, v194
	v_cvt_pk_bf16_f32 v10, v10, v11
	v_cvt_pk_bf16_f32 v11, v84, v85
	s_waitcnt lgkmcnt(3)
	v_mfma_f32_32x32x16_bf16 v[32:47], v[96:99], v[12:15], v[32:47]
	v_add_f32_e64 v2, v184, v2
	v_add_f32_e64 v3, v185, v3
	v_add_f32_e64 v4, v188, v4
	v_add_f32_e64 v5, v189, v5
	s_waitcnt lgkmcnt(2)
	v_mfma_f32_32x32x16_bf16 v[16:31], v[100:103], v[12:15], v[16:31]
	ds_read_b64_tr_b16 v[12:13], v198 offset:8192
	ds_read_b64_tr_b16 v[84:85], v199 offset:8192
	ds_read_b64_tr_b16 v[96:97], v200 offset:8192
	ds_read_b64_tr_b16 v[14:15], v198 offset:10240
	ds_read_b64_tr_b16 v[86:87], v199 offset:10240
	ds_read_b64_tr_b16 v[98:99], v200 offset:10240
	s_waitcnt lgkmcnt(6)
	v_mfma_f32_32x32x16_bf16 v[64:79], v[80:83], v[8:11], v[64:79]
	v_fmamk_f32 v80, v90, 0x3e38aa3b, v165
	v_exp_f32_e32 v101, v80
	v_fmamk_f32 v80, v91, 0x3e38aa3b, v165
	v_exp_f32_e32 v100, v80
	v_fmamk_f32 v80, v92, 0x3e38aa3b, v165
	v_exp_f32_e32 v103, v80
	v_fmamk_f32 v80, v93, 0x3e38aa3b, v165
	s_waitcnt lgkmcnt(2)
	v_mfma_f32_32x32x16_bf16 v[48:63], v[12:15], v[8:11], v[48:63]
	v_fmamk_f32 v12, v94, 0x3e38aa3b, v165
	v_fmac_f32_e32 v165, 0x3e38aa3b, v95
	v_exp_f32_e32 v102, v80
	v_exp_f32_e32 v93, v12
	v_exp_f32_e32 v92, v165
	v_pk_mov_b32 v[12:13], v[188:189], v[188:189] op_sel:[1,0]
	v_pk_mov_b32 v[14:15], v[100:101], v[100:101] op_sel:[1,0]
	v_cvt_pk_bf16_f32 v12, v12, v13
	s_waitcnt lgkmcnt(1)
	v_mfma_f32_32x32x16_bf16 v[32:47], v[84:87], v[8:11], v[32:47]
	v_cvt_pk_bf16_f32 v13, v14, v15
	v_pk_mov_b32 v[14:15], v[102:103], v[102:103] op_sel:[1,0]
	v_pk_mov_b32 v[84:85], v[92:93], v[92:93] op_sel:[1,0]
	v_cvt_pk_bf16_f32 v14, v14, v15
	ds_read_b64_tr_b16 v[80:81], v0 offset:12288
	ds_read_b64_tr_b16 v[82:83], v0 offset:14336
	v_cvt_pk_bf16_f32 v15, v84, v85
	v_add_f32_e32 v94, 0, v190
	s_waitcnt lgkmcnt(2)
	v_mfma_f32_32x32x16_bf16 v[16:31], v[96:99], v[8:11], v[16:31]
	ds_read_b64_tr_b16 v[8:9], v198 offset:12288
	ds_read_b64_tr_b16 v[84:85], v199 offset:12288
	ds_read_b64_tr_b16 v[88:89], v200 offset:12288
	ds_read_b64_tr_b16 v[10:11], v198 offset:14336
	ds_read_b64_tr_b16 v[86:87], v199 offset:14336
	ds_read_b64_tr_b16 v[90:91], v200 offset:14336
	v_add_f32_e32 v94, v196, v94
	v_pk_add_f32 v[92:93], v[92:93], v[108:109]
	s_waitcnt lgkmcnt(2)
	v_mfma_f32_32x32x16_bf16 v[48:63], v[8:11], v[12:15], v[48:63]
	v_add_f32_e32 v8, v197, v94
	v_add_f32_e32 v8, v193, v8
	v_add_f32_e32 v8, v111, v8
	v_add_f32_e32 v8, v110, v8
	v_add_f32_e32 v3, v3, v8
	v_add_f32_e32 v2, v2, v3
	v_add_f32_e32 v2, v5, v2
	v_mfma_f32_32x32x16_bf16 v[64:79], v[80:83], v[12:15], v[64:79]
	v_add_f32_e64 v80, v100, v104
	v_add_f32_e64 v81, v101, v105
	v_add_f32_e32 v2, v4, v2
	v_add_f32_e32 v2, v81, v2
	v_add_f32_e64 v82, v102, v106
	v_add_f32_e64 v83, v103, v107
	v_add_f32_e32 v2, v80, v2
	v_add_f32_e32 v2, v83, v2
	v_add_f32_e32 v2, v82, v2
	s_waitcnt lgkmcnt(1)
	v_mfma_f32_32x32x16_bf16 v[32:47], v[84:87], v[12:15], v[32:47]
	v_add_f32_e32 v2, v93, v2
	v_add_f32_e32 v2, v92, v2
	v_add_f32_e32 v182, v2, v182
	s_waitcnt lgkmcnt(0)
	v_mfma_f32_32x32x16_bf16 v[16:31], v[88:91], v[12:15], v[16:31]
	s_cmp_ge_u32 s2, s3
	s_cbranch_scc0 .LBB0_122

.Lattn_pair:
	v_xor_b32_e32 v225, 64, v0
	v_xor_b32_e32 v248, 0xc0, v0
	ds_read_b128 v[2:5], v6
	ds_read_b128 v[8:11], v6 offset:8704
	ds_read_b128 v[12:15], v6 offset:32
	ds_read_b128 v[226:229], v6 offset:8736
	s_waitcnt lgkmcnt(3)
	v_mfma_f32_32x32x16_bf16 v[96:111], v[2:5], v[112:115], 0
	ds_read_b128 v[2:5], v6 offset:64
	s_waitcnt lgkmcnt(3)
	v_mfma_f32_32x32x16_bf16 v[80:95], v[8:11], v[112:115], 0
	ds_read_b128 v[8:11], v6 offset:8768
	s_waitcnt lgkmcnt(3)
	v_mfma_f32_32x32x16_bf16 v[96:111], v[12:15], v[116:119], v[96:111]
	ds_read_b128 v[12:15], v6 offset:96
	s_waitcnt lgkmcnt(3)
	v_mfma_f32_32x32x16_bf16 v[80:95], v[226:229], v[116:119], v[80:95]
	ds_read_b128 v[226:229], v6 offset:8800
	s_waitcnt lgkmcnt(3)
	v_mfma_f32_32x32x16_bf16 v[96:111], v[2:5], v[120:123], v[96:111]
	ds_read_b128 v[2:5], v6 offset:17408
	s_waitcnt lgkmcnt(3)
	v_mfma_f32_32x32x16_bf16 v[80:95], v[8:11], v[120:123], v[80:95]
	ds_read_b128 v[8:11], v6 offset:26112
	s_waitcnt lgkmcnt(3)
	v_mfma_f32_32x32x16_bf16 v[96:111], v[12:15], v[124:127], v[96:111]
	ds_read_b128 v[12:15], v6 offset:17440
	s_waitcnt lgkmcnt(3)
	v_mfma_f32_32x32x16_bf16 v[80:95], v[226:229], v[124:127], v[80:95]
	ds_read_b128 v[226:229], v6 offset:26144
	s_nop 11
	v_max3_f32 v238, v96, v97, v98
	v_max3_f32 v241, v99, v100, v101
	v_max3_f32 v246, v102, v103, v104
	v_max3_f32 v247, v105, v106, v107
	v_max3_f32 v238, v238, v108, v109
	v_max3_f32 v241, v241, v110, v111
	v_max3_f32 v246, v246, v80, v81
	v_max3_f32 v247, v247, v82, v83
	v_max3_f32 v238, v238, v84, v85
	v_max3_f32 v241, v241, v86, v87
	v_max3_f32 v246, v246, v88, v89
	v_max3_f32 v247, v247, v90, v91
	v_max3_f32 v238, v238, v92, v93
	v_max3_f32 v241, v241, v94, v95
	v_max3_f32 v238, v238, v241, v246
	v_max_f32_e32 v238, v238, v247
	v_and_b32_e32 v246, 64, v220
	v_xor_b32_e32 v247, 32, v220
	v_add_u32_e32 v246, 64, v246
	v_cmp_lt_i32_e32 vcc, v247, v246
	s_nop 1
	v_cndmask_b32_e32 v247, v220, v247, vcc
	v_lshlrev_b32_e32 v247, 2, v247
	ds_bpermute_b32 v241, v247, v238
	s_waitcnt lgkmcnt(0)
	v_max3_f32 v7, v183, v238, v241
	v_cmp_gt_f32_e32 vcc, v7, v183
	s_cbranch_vccz .Lattn_pair_nra
	v_sub_f32_e32 v246, v183, v7
	v_mul_f32_e32 v246, 0x3e38aa3b, v246
	v_exp_f32_e32 v246, v246
	s_nop 0
	v_pk_mul_f32 v[78:79], v[78:79], v[246:247] op_sel_hi:[1,0]
	v_pk_mul_f32 v[76:77], v[76:77], v[246:247] op_sel_hi:[1,0]
	v_pk_mul_f32 v[74:75], v[74:75], v[246:247] op_sel_hi:[1,0]
	v_pk_mul_f32 v[72:73], v[72:73], v[246:247] op_sel_hi:[1,0]
	v_pk_mul_f32 v[70:71], v[70:71], v[246:247] op_sel_hi:[1,0]
	v_pk_mul_f32 v[68:69], v[68:69], v[246:247] op_sel_hi:[1,0]
	v_pk_mul_f32 v[66:67], v[66:67], v[246:247] op_sel_hi:[1,0]
	v_pk_mul_f32 v[64:65], v[64:65], v[246:247] op_sel_hi:[1,0]
	v_pk_mul_f32 v[62:63], v[62:63], v[246:247] op_sel_hi:[1,0]
	v_pk_mul_f32 v[60:61], v[60:61], v[246:247] op_sel_hi:[1,0]
	v_pk_mul_f32 v[58:59], v[58:59], v[246:247] op_sel_hi:[1,0]
	v_pk_mul_f32 v[56:57], v[56:57], v[246:247] op_sel_hi:[1,0]
	v_pk_mul_f32 v[54:55], v[54:55], v[246:247] op_sel_hi:[1,0]
	v_pk_mul_f32 v[52:53], v[52:53], v[246:247] op_sel_hi:[1,0]
	v_pk_mul_f32 v[50:51], v[50:51], v[246:247] op_sel_hi:[1,0]
	v_pk_mul_f32 v[48:49], v[48:49], v[246:247] op_sel_hi:[1,0]
	v_pk_mul_f32 v[46:47], v[46:47], v[246:247] op_sel_hi:[1,0]
	v_pk_mul_f32 v[44:45], v[44:45], v[246:247] op_sel_hi:[1,0]
	v_pk_mul_f32 v[42:43], v[42:43], v[246:247] op_sel_hi:[1,0]
	v_pk_mul_f32 v[40:41], v[40:41], v[246:247] op_sel_hi:[1,0]
	v_pk_mul_f32 v[38:39], v[38:39], v[246:247] op_sel_hi:[1,0]
	v_pk_mul_f32 v[36:37], v[36:37], v[246:247] op_sel_hi:[1,0]
	v_pk_mul_f32 v[34:35], v[34:35], v[246:247] op_sel_hi:[1,0]
	v_pk_mul_f32 v[32:33], v[32:33], v[246:247] op_sel_hi:[1,0]
	v_pk_mul_f32 v[30:31], v[30:31], v[246:247] op_sel_hi:[1,0]
	v_pk_mul_f32 v[28:29], v[28:29], v[246:247] op_sel_hi:[1,0]
	v_pk_mul_f32 v[26:27], v[26:27], v[246:247] op_sel_hi:[1,0]
	v_pk_mul_f32 v[24:25], v[24:25], v[246:247] op_sel_hi:[1,0]
	v_pk_mul_f32 v[22:23], v[22:23], v[246:247] op_sel_hi:[1,0]
	v_pk_mul_f32 v[20:21], v[20:21], v[246:247] op_sel_hi:[1,0]
	v_pk_mul_f32 v[18:19], v[18:19], v[246:247] op_sel_hi:[1,0]
	v_pk_mul_f32 v[16:17], v[16:17], v[246:247] op_sel_hi:[1,0]
	v_mul_f32_e32 v182, v182, v246
.Lattn_pair_nra:
	v_mul_f32_e32 v165, 0xbe38aa3b, v7
	s_waitcnt lgkmcnt(4)
	v_mfma_f32_32x32x16_bf16 v[184:199], v[2:5], v[112:115], 0
	ds_read_b128 v[2:5], v6 offset:17472
	v_fmamk_f32 v96, v96, 0x3e38aa3b, v165
	v_fmamk_f32 v97, v97, 0x3e38aa3b, v165
	v_fmamk_f32 v98, v98, 0x3e38aa3b, v165
	v_fmamk_f32 v99, v99, 0x3e38aa3b, v165
	v_exp_f32_e32 v96, v96
	v_exp_f32_e32 v97, v97
	v_exp_f32_e32 v98, v98
	v_exp_f32_e32 v99, v99
	v_add_f32_e32 v238, v96, v97
	v_add_f32_e32 v241, v98, v99
	v_cvt_pk_bf16_f32 v96, v96, v97
	v_cvt_pk_bf16_f32 v97, v98, v99
	s_waitcnt lgkmcnt(4)
	v_mfma_f32_32x32x16_bf16 v[200:215], v[8:11], v[112:115], 0
	ds_read_b128 v[8:11], v6 offset:26176
	v_fmamk_f32 v100, v100, 0x3e38aa3b, v165
	v_fmamk_f32 v101, v101, 0x3e38aa3b, v165
	v_fmamk_f32 v102, v102, 0x3e38aa3b, v165
	v_fmamk_f32 v103, v103, 0x3e38aa3b, v165
	v_exp_f32_e32 v100, v100
	v_exp_f32_e32 v101, v101
	v_exp_f32_e32 v102, v102
	v_exp_f32_e32 v103, v103
	v_add_f32_e32 v246, v100, v101
	v_add_f32_e32 v247, v102, v103
	v_add_f32_e32 v238, v238, v246
	v_add_f32_e32 v241, v241, v247
	v_cvt_pk_bf16_f32 v98, v100, v101
	v_cvt_pk_bf16_f32 v99, v102, v103
	s_waitcnt lgkmcnt(4)
	v_mfma_f32_32x32x16_bf16 v[184:199], v[12:15], v[116:119], v[184:199]
	ds_read_b128 v[12:15], v6 offset:17504
	v_fmamk_f32 v104, v104, 0x3e38aa3b, v165
	v_fmamk_f32 v105, v105, 0x3e38aa3b, v165
	v_fmamk_f32 v106, v106, 0x3e38aa3b, v165
	v_fmamk_f32 v107, v107, 0x3e38aa3b, v165
	v_exp_f32_e32 v104, v104
	v_exp_f32_e32 v105, v105
	v_exp_f32_e32 v106, v106
	v_exp_f32_e32 v107, v107
	v_add_f32_e32 v246, v104, v105
	v_add_f32_e32 v247, v106, v107
	v_add_f32_e32 v238, v238, v246
	v_add_f32_e32 v241, v241, v247
	v_cvt_pk_bf16_f32 v104, v104, v105
	v_cvt_pk_bf16_f32 v105, v106, v107
	s_waitcnt lgkmcnt(4)
	v_mfma_f32_32x32x16_bf16 v[200:215], v[226:229], v[116:119], v[200:215]
	ds_read_b128 v[226:229], v6 offset:26208
	v_fmamk_f32 v108, v108, 0x3e38aa3b, v165
	v_fmamk_f32 v109, v109, 0x3e38aa3b, v165
	v_fmamk_f32 v110, v110, 0x3e38aa3b, v165
	v_fmamk_f32 v111, v111, 0x3e38aa3b, v165
	v_exp_f32_e32 v108, v108
	v_exp_f32_e32 v109, v109
	v_exp_f32_e32 v110, v110
	v_exp_f32_e32 v111, v111
	v_add_f32_e32 v246, v108, v109
	v_add_f32_e32 v247, v110, v111
	v_add_f32_e32 v238, v238, v246
	v_add_f32_e32 v241, v241, v247
	v_cvt_pk_bf16_f32 v106, v108, v109
	v_cvt_pk_bf16_f32 v107, v110, v111
	s_waitcnt lgkmcnt(3)
	v_mfma_f32_32x32x16_bf16 v[184:199], v[2:5], v[120:123], v[184:199]
	v_xor_b32_e32 v6, 0x80, v0
	ds_read_b64_tr_b16 v[230:231], v0
	ds_read_b64_tr_b16 v[232:233], v0 offset:2048
	v_fmamk_f32 v80, v80, 0x3e38aa3b, v165
	v_fmamk_f32 v81, v81, 0x3e38aa3b, v165
	v_fmamk_f32 v82, v82, 0x3e38aa3b, v165
	v_fmamk_f32 v83, v83, 0x3e38aa3b, v165
	v_exp_f32_e32 v80, v80
	v_exp_f32_e32 v81, v81
	v_exp_f32_e32 v82, v82
	v_exp_f32_e32 v83, v83
	v_add_f32_e32 v246, v80, v81
	v_add_f32_e32 v247, v82, v83
	v_add_f32_e32 v238, v238, v246
	v_add_f32_e32 v241, v241, v247
	v_cvt_pk_bf16_f32 v80, v80, v81
	v_cvt_pk_bf16_f32 v81, v82, v83
	s_waitcnt lgkmcnt(4)
	v_mfma_f32_32x32x16_bf16 v[200:215], v[8:11], v[120:123], v[200:215]
	ds_read_b64_tr_b16 v[234:235], v225
	ds_read_b64_tr_b16 v[236:237], v225 offset:2048
	v_fmamk_f32 v84, v84, 0x3e38aa3b, v165
	v_fmamk_f32 v85, v85, 0x3e38aa3b, v165
	v_fmamk_f32 v86, v86, 0x3e38aa3b, v165
	v_fmamk_f32 v87, v87, 0x3e38aa3b, v165
	v_exp_f32_e32 v84, v84
	v_exp_f32_e32 v85, v85
	v_exp_f32_e32 v86, v86
	v_exp_f32_e32 v87, v87
	v_add_f32_e32 v246, v84, v85
	v_add_f32_e32 v247, v86, v87
	v_add_f32_e32 v238, v238, v246
	v_add_f32_e32 v241, v241, v247
	v_cvt_pk_bf16_f32 v82, v84, v85
	v_cvt_pk_bf16_f32 v83, v86, v87
	s_waitcnt lgkmcnt(5)
	v_mfma_f32_32x32x16_bf16 v[184:199], v[12:15], v[124:127], v[184:199]
	ds_read_b64_tr_b16 v[242:243], v6
	ds_read_b64_tr_b16 v[244:245], v6 offset:2048
	v_fmamk_f32 v88, v88, 0x3e38aa3b, v165
	v_fmamk_f32 v89, v89, 0x3e38aa3b, v165
	v_fmamk_f32 v90, v90, 0x3e38aa3b, v165
	v_fmamk_f32 v91, v91, 0x3e38aa3b, v165
	v_exp_f32_e32 v88, v88
	v_exp_f32_e32 v89, v89
	v_exp_f32_e32 v90, v90
	v_exp_f32_e32 v91, v91
	v_add_f32_e32 v246, v88, v89
	v_add_f32_e32 v247, v90, v91
	v_add_f32_e32 v238, v238, v246
	v_add_f32_e32 v241, v241, v247
	v_cvt_pk_bf16_f32 v88, v88, v89
	v_cvt_pk_bf16_f32 v89, v90, v91
	s_waitcnt lgkmcnt(6)
	v_mfma_f32_32x32x16_bf16 v[200:215], v[226:229], v[124:127], v[200:215]
	ds_read_b64_tr_b16 v[2:3], v248
	ds_read_b64_tr_b16 v[4:5], v248 offset:2048
	v_fmamk_f32 v92, v92, 0x3e38aa3b, v165
	v_fmamk_f32 v93, v93, 0x3e38aa3b, v165
	v_fmamk_f32 v94, v94, 0x3e38aa3b, v165
	v_fmamk_f32 v95, v95, 0x3e38aa3b, v165
	v_exp_f32_e32 v92, v92
	v_exp_f32_e32 v93, v93
	v_exp_f32_e32 v94, v94
	v_exp_f32_e32 v95, v95
	v_add_f32_e32 v246, v92, v93
	v_add_f32_e32 v247, v94, v95
	v_add_f32_e32 v238, v238, v246
	v_add_f32_e32 v241, v241, v247
	v_cvt_pk_bf16_f32 v90, v92, v93
	v_cvt_pk_bf16_f32 v91, v94, v95
	v_add_f32_e32 v238, v238, v241
	v_add_f32_e32 v182, v182, v238
	s_waitcnt lgkmcnt(6)
	v_mfma_f32_32x32x16_bf16 v[64:79], v[230:233], v[96:99], v[64:79]
	ds_read_b64_tr_b16 v[8:9], v0 offset:4096
	ds_read_b64_tr_b16 v[10:11], v0 offset:6144
	s_waitcnt lgkmcnt(6)
	v_mfma_f32_32x32x16_bf16 v[48:63], v[234:237], v[96:99], v[48:63]
	ds_read_b64_tr_b16 v[12:13], v225 offset:4096
	ds_read_b64_tr_b16 v[14:15], v225 offset:6144
	s_waitcnt lgkmcnt(6)
	v_mfma_f32_32x32x16_bf16 v[32:47], v[242:245], v[96:99], v[32:47]
	ds_read_b64_tr_b16 v[226:227], v6 offset:4096
	ds_read_b64_tr_b16 v[228:229], v6 offset:6144
	v_max3_f32 v238, v184, v185, v186
	v_max3_f32 v241, v187, v188, v189
	v_max3_f32 v246, v190, v191, v192
	v_max3_f32 v247, v193, v194, v195
	v_max3_f32 v238, v238, v196, v197
	v_max3_f32 v241, v241, v198, v199
	v_max3_f32 v246, v246, v200, v201
	v_max3_f32 v247, v247, v202, v203
	s_waitcnt lgkmcnt(6)
	v_mfma_f32_32x32x16_bf16 v[16:31], v[2:5], v[96:99], v[16:31]
	ds_read_b64_tr_b16 v[230:231], v248 offset:4096
	ds_read_b64_tr_b16 v[232:233], v248 offset:6144
	v_max3_f32 v238, v238, v204, v205
	v_max3_f32 v241, v241, v206, v207
	v_max3_f32 v246, v246, v208, v209
	v_max3_f32 v247, v247, v210, v211
	v_max3_f32 v238, v238, v212, v213
	v_max3_f32 v241, v241, v214, v215
	v_max3_f32 v238, v238, v241, v246
	v_max_f32_e32 v238, v238, v247
	v_and_b32_e32 v246, 64, v220
	v_xor_b32_e32 v247, 32, v220
	v_add_u32_e32 v246, 64, v246
	v_cmp_lt_i32_e32 vcc, v247, v246
	s_nop 1
	v_cndmask_b32_e32 v247, v220, v247, vcc
	v_lshlrev_b32_e32 v247, 2, v247
	ds_bpermute_b32 v241, v247, v238
	s_waitcnt lgkmcnt(7)
	v_mfma_f32_32x32x16_bf16 v[64:79], v[8:11], v[104:107], v[64:79]
	ds_read_b64_tr_b16 v[234:235], v0 offset:8192
	ds_read_b64_tr_b16 v[236:237], v0 offset:10240
	s_waitcnt lgkmcnt(7)
	v_mfma_f32_32x32x16_bf16 v[48:63], v[12:15], v[104:107], v[48:63]
	ds_read_b64_tr_b16 v[242:243], v225 offset:8192
	ds_read_b64_tr_b16 v[244:245], v225 offset:10240
	s_waitcnt lgkmcnt(4)
	v_max3_f32 v183, v7, v238, v241
	v_mul_f32_e32 v165, 0xbe38aa3b, v183
	s_waitcnt lgkmcnt(7)
	v_mfma_f32_32x32x16_bf16 v[32:47], v[226:229], v[104:107], v[32:47]
	ds_read_b64_tr_b16 v[2:3], v6 offset:8192
	ds_read_b64_tr_b16 v[4:5], v6 offset:10240
	v_fmamk_f32 v184, v184, 0x3e38aa3b, v165
	v_fmamk_f32 v185, v185, 0x3e38aa3b, v165
	v_fmamk_f32 v186, v186, 0x3e38aa3b, v165
	v_fmamk_f32 v187, v187, 0x3e38aa3b, v165
	v_exp_f32_e32 v184, v184
	v_exp_f32_e32 v185, v185
	v_exp_f32_e32 v186, v186
	v_exp_f32_e32 v187, v187
	v_add_f32_e32 v238, v184, v185
	v_add_f32_e32 v241, v186, v187
	v_cvt_pk_bf16_f32 v184, v184, v185
	v_cvt_pk_bf16_f32 v185, v186, v187
	s_waitcnt lgkmcnt(7)
	v_mfma_f32_32x32x16_bf16 v[16:31], v[230:233], v[104:107], v[16:31]
	ds_read_b64_tr_b16 v[8:9], v248 offset:8192
	ds_read_b64_tr_b16 v[10:11], v248 offset:10240
	v_fmamk_f32 v188, v188, 0x3e38aa3b, v165
	v_fmamk_f32 v189, v189, 0x3e38aa3b, v165
	v_fmamk_f32 v190, v190, 0x3e38aa3b, v165
	v_fmamk_f32 v191, v191, 0x3e38aa3b, v165
	v_exp_f32_e32 v188, v188
	v_exp_f32_e32 v189, v189
	v_exp_f32_e32 v190, v190
	v_exp_f32_e32 v191, v191
	v_add_f32_e32 v246, v188, v189
	v_add_f32_e32 v247, v190, v191
	v_add_f32_e32 v238, v238, v246
	v_add_f32_e32 v241, v241, v247
	v_cvt_pk_bf16_f32 v186, v188, v189
	v_cvt_pk_bf16_f32 v187, v190, v191
	s_waitcnt lgkmcnt(6)
	v_mfma_f32_32x32x16_bf16 v[64:79], v[234:237], v[80:83], v[64:79]
	ds_read_b64_tr_b16 v[12:13], v0 offset:12288
	ds_read_b64_tr_b16 v[14:15], v0 offset:14336
	v_fmamk_f32 v192, v192, 0x3e38aa3b, v165
	v_fmamk_f32 v193, v193, 0x3e38aa3b, v165
	v_fmamk_f32 v194, v194, 0x3e38aa3b, v165
	v_fmamk_f32 v195, v195, 0x3e38aa3b, v165
	v_exp_f32_e32 v192, v192
	v_exp_f32_e32 v193, v193
	v_exp_f32_e32 v194, v194
	v_exp_f32_e32 v195, v195
	v_add_f32_e32 v246, v192, v193
	v_add_f32_e32 v247, v194, v195
	v_add_f32_e32 v238, v238, v246
	v_add_f32_e32 v241, v241, v247
	v_cvt_pk_bf16_f32 v192, v192, v193
	v_cvt_pk_bf16_f32 v193, v194, v195
	s_waitcnt lgkmcnt(6)
	v_mfma_f32_32x32x16_bf16 v[48:63], v[242:245], v[80:83], v[48:63]
	ds_read_b64_tr_b16 v[226:227], v225 offset:12288
	ds_read_b64_tr_b16 v[228:229], v225 offset:14336
	v_fmamk_f32 v196, v196, 0x3e38aa3b, v165
	v_fmamk_f32 v197, v197, 0x3e38aa3b, v165
	v_fmamk_f32 v198, v198, 0x3e38aa3b, v165
	v_fmamk_f32 v199, v199, 0x3e38aa3b, v165
	v_exp_f32_e32 v196, v196
	v_exp_f32_e32 v197, v197
	v_exp_f32_e32 v198, v198
	v_exp_f32_e32 v199, v199
	v_add_f32_e32 v246, v196, v197
	v_add_f32_e32 v247, v198, v199
	v_add_f32_e32 v238, v238, v246
	v_add_f32_e32 v241, v241, v247
	v_cvt_pk_bf16_f32 v194, v196, v197
	v_cvt_pk_bf16_f32 v195, v198, v199
	s_waitcnt lgkmcnt(6)
	v_mfma_f32_32x32x16_bf16 v[32:47], v[2:5], v[80:83], v[32:47]
	ds_read_b64_tr_b16 v[230:231], v6 offset:12288
	ds_read_b64_tr_b16 v[232:233], v6 offset:14336
	v_fmamk_f32 v200, v200, 0x3e38aa3b, v165
	v_fmamk_f32 v201, v201, 0x3e38aa3b, v165
	v_fmamk_f32 v202, v202, 0x3e38aa3b, v165
	v_fmamk_f32 v203, v203, 0x3e38aa3b, v165
	v_exp_f32_e32 v200, v200
	v_exp_f32_e32 v201, v201
	v_exp_f32_e32 v202, v202
	v_exp_f32_e32 v203, v203
	v_add_f32_e32 v246, v200, v201
	v_add_f32_e32 v247, v202, v203
	v_add_f32_e32 v238, v238, v246
	v_add_f32_e32 v241, v241, v247
	v_cvt_pk_bf16_f32 v200, v200, v201
	v_cvt_pk_bf16_f32 v201, v202, v203
	s_waitcnt lgkmcnt(6)
	v_mfma_f32_32x32x16_bf16 v[16:31], v[8:11], v[80:83], v[16:31]
	ds_read_b64_tr_b16 v[234:235], v248 offset:12288
	ds_read_b64_tr_b16 v[236:237], v248 offset:14336
	v_fmamk_f32 v204, v204, 0x3e38aa3b, v165
	v_fmamk_f32 v205, v205, 0x3e38aa3b, v165
	v_fmamk_f32 v206, v206, 0x3e38aa3b, v165
	v_fmamk_f32 v207, v207, 0x3e38aa3b, v165
	v_exp_f32_e32 v204, v204
	v_exp_f32_e32 v205, v205
	v_exp_f32_e32 v206, v206
	v_exp_f32_e32 v207, v207
	v_add_f32_e32 v246, v204, v205
	v_add_f32_e32 v247, v206, v207
	v_add_f32_e32 v238, v238, v246
	v_add_f32_e32 v241, v241, v247
	v_cvt_pk_bf16_f32 v202, v204, v205
	v_cvt_pk_bf16_f32 v203, v206, v207
	s_waitcnt lgkmcnt(6)
	v_mfma_f32_32x32x16_bf16 v[64:79], v[12:15], v[88:91], v[64:79]
	ds_read_b64_tr_b16 v[242:243], v0 offset:16384
	ds_read_b64_tr_b16 v[244:245], v0 offset:18432
	v_fmamk_f32 v208, v208, 0x3e38aa3b, v165
	v_fmamk_f32 v209, v209, 0x3e38aa3b, v165
	v_fmamk_f32 v210, v210, 0x3e38aa3b, v165
	v_fmamk_f32 v211, v211, 0x3e38aa3b, v165
	v_exp_f32_e32 v208, v208
	v_exp_f32_e32 v209, v209
	v_exp_f32_e32 v210, v210
	v_exp_f32_e32 v211, v211
	v_add_f32_e32 v246, v208, v209
	v_add_f32_e32 v247, v210, v211
	v_add_f32_e32 v238, v238, v246
	v_add_f32_e32 v241, v241, v247
	v_cvt_pk_bf16_f32 v208, v208, v209
	v_cvt_pk_bf16_f32 v209, v210, v211
	s_waitcnt lgkmcnt(6)
	v_mfma_f32_32x32x16_bf16 v[48:63], v[226:229], v[88:91], v[48:63]
	ds_read_b64_tr_b16 v[2:3], v225 offset:16384
	ds_read_b64_tr_b16 v[4:5], v225 offset:18432
	v_fmamk_f32 v212, v212, 0x3e38aa3b, v165
	v_fmamk_f32 v213, v213, 0x3e38aa3b, v165
	v_fmamk_f32 v214, v214, 0x3e38aa3b, v165
	v_fmamk_f32 v215, v215, 0x3e38aa3b, v165
	v_exp_f32_e32 v212, v212
	v_exp_f32_e32 v213, v213
	v_exp_f32_e32 v214, v214
	v_exp_f32_e32 v215, v215
	v_add_f32_e32 v246, v212, v213
	v_add_f32_e32 v247, v214, v215
	v_add_f32_e32 v238, v238, v246
	v_add_f32_e32 v241, v241, v247
	v_cvt_pk_bf16_f32 v210, v212, v213
	v_cvt_pk_bf16_f32 v211, v214, v215
	s_waitcnt lgkmcnt(6)
	v_mfma_f32_32x32x16_bf16 v[32:47], v[230:233], v[88:91], v[32:47]
	ds_read_b64_tr_b16 v[8:9], v6 offset:16384
	ds_read_b64_tr_b16 v[10:11], v6 offset:18432
	s_waitcnt lgkmcnt(6)
	v_mfma_f32_32x32x16_bf16 v[16:31], v[234:237], v[88:91], v[16:31]
	ds_read_b64_tr_b16 v[12:13], v248 offset:16384
	ds_read_b64_tr_b16 v[14:15], v248 offset:18432
	v_add_f32_e32 v238, v238, v241
	v_cmp_gt_f32_e32 vcc, v183, v7
	s_cbranch_vccz .Lattn_pair_nrb
	s_nop 15
	v_sub_f32_e32 v246, v7, v183
	v_mul_f32_e32 v246, 0x3e38aa3b, v246
	v_exp_f32_e32 v246, v246
	s_nop 0
	v_pk_mul_f32 v[78:79], v[78:79], v[246:247] op_sel_hi:[1,0]
	v_pk_mul_f32 v[76:77], v[76:77], v[246:247] op_sel_hi:[1,0]
	v_pk_mul_f32 v[74:75], v[74:75], v[246:247] op_sel_hi:[1,0]
	v_pk_mul_f32 v[72:73], v[72:73], v[246:247] op_sel_hi:[1,0]
	v_pk_mul_f32 v[70:71], v[70:71], v[246:247] op_sel_hi:[1,0]
	v_pk_mul_f32 v[68:69], v[68:69], v[246:247] op_sel_hi:[1,0]
	v_pk_mul_f32 v[66:67], v[66:67], v[246:247] op_sel_hi:[1,0]
	v_pk_mul_f32 v[64:65], v[64:65], v[246:247] op_sel_hi:[1,0]
	v_pk_mul_f32 v[62:63], v[62:63], v[246:247] op_sel_hi:[1,0]
	v_pk_mul_f32 v[60:61], v[60:61], v[246:247] op_sel_hi:[1,0]
	v_pk_mul_f32 v[58:59], v[58:59], v[246:247] op_sel_hi:[1,0]
	v_pk_mul_f32 v[56:57], v[56:57], v[246:247] op_sel_hi:[1,0]
	v_pk_mul_f32 v[54:55], v[54:55], v[246:247] op_sel_hi:[1,0]
	v_pk_mul_f32 v[52:53], v[52:53], v[246:247] op_sel_hi:[1,0]
	v_pk_mul_f32 v[50:51], v[50:51], v[246:247] op_sel_hi:[1,0]
	v_pk_mul_f32 v[48:49], v[48:49], v[246:247] op_sel_hi:[1,0]
	v_pk_mul_f32 v[46:47], v[46:47], v[246:247] op_sel_hi:[1,0]
	v_pk_mul_f32 v[44:45], v[44:45], v[246:247] op_sel_hi:[1,0]
	v_pk_mul_f32 v[42:43], v[42:43], v[246:247] op_sel_hi:[1,0]
	v_pk_mul_f32 v[40:41], v[40:41], v[246:247] op_sel_hi:[1,0]
	v_pk_mul_f32 v[38:39], v[38:39], v[246:247] op_sel_hi:[1,0]
	v_pk_mul_f32 v[36:37], v[36:37], v[246:247] op_sel_hi:[1,0]
	v_pk_mul_f32 v[34:35], v[34:35], v[246:247] op_sel_hi:[1,0]
	v_pk_mul_f32 v[32:33], v[32:33], v[246:247] op_sel_hi:[1,0]
	v_pk_mul_f32 v[30:31], v[30:31], v[246:247] op_sel_hi:[1,0]
	v_pk_mul_f32 v[28:29], v[28:29], v[246:247] op_sel_hi:[1,0]
	v_pk_mul_f32 v[26:27], v[26:27], v[246:247] op_sel_hi:[1,0]
	v_pk_mul_f32 v[24:25], v[24:25], v[246:247] op_sel_hi:[1,0]
	v_pk_mul_f32 v[22:23], v[22:23], v[246:247] op_sel_hi:[1,0]
	v_pk_mul_f32 v[20:21], v[20:21], v[246:247] op_sel_hi:[1,0]
	v_pk_mul_f32 v[18:19], v[18:19], v[246:247] op_sel_hi:[1,0]
	v_pk_mul_f32 v[16:17], v[16:17], v[246:247] op_sel_hi:[1,0]
	v_mul_f32_e32 v182, v182, v246
.Lattn_pair_nrb:
	v_add_f32_e32 v182, v182, v238
	s_add_i32 s14, s12, 2
	s_cmp_gt_u32 s14, s10
	s_cbranch_scc1 .Lattn_pair_b6plain
	s_and_b32 s14, s13, 1
	s_mul_i32 s15, s14, 0x8800
	s_mul_i32 s14, s14, 0x9000
	v_add3_u32 v246, v176, s15, v174
	v_add3_u32 v247, v177, s14, v175
	s_waitcnt lgkmcnt(6)
	v_mfma_f32_32x32x16_bf16 v[64:79], v[242:245], v[184:187], v[64:79]
	ds_read_b64_tr_b16 v[226:227], v0 offset:20480
	ds_read_b64_tr_b16 v[228:229], v0 offset:22528
	s_waitcnt vmcnt(7)
	ds_write_b128 v246, v[128:131]
	s_waitcnt lgkmcnt(7)
	v_mfma_f32_32x32x16_bf16 v[48:63], v[2:5], v[184:187], v[48:63]
	ds_read_b64_tr_b16 v[230:231], v225 offset:20480
	ds_read_b64_tr_b16 v[232:233], v225 offset:22528
	s_waitcnt vmcnt(6)
	ds_write_b128 v247, v[132:135]
	s_waitcnt lgkmcnt(8)
	v_mfma_f32_32x32x16_bf16 v[32:47], v[8:11], v[184:187], v[32:47]
	ds_read_b64_tr_b16 v[234:235], v6 offset:20480
	ds_read_b64_tr_b16 v[236:237], v6 offset:22528
	s_waitcnt vmcnt(5)
	ds_write_b128 v246, v[136:139] offset:8704
	s_waitcnt lgkmcnt(9)
	v_mfma_f32_32x32x16_bf16 v[16:31], v[12:15], v[184:187], v[16:31]
	ds_read_b64_tr_b16 v[242:243], v248 offset:20480
	ds_read_b64_tr_b16 v[244:245], v248 offset:22528
	s_waitcnt vmcnt(4)
	ds_write_b128 v247, v[140:143] offset:8192
	s_waitcnt lgkmcnt(10)
	v_mfma_f32_32x32x16_bf16 v[64:79], v[226:229], v[192:195], v[64:79]
	ds_read_b64_tr_b16 v[2:3], v0 offset:24576
	ds_read_b64_tr_b16 v[4:5], v0 offset:26624
	s_waitcnt vmcnt(3)
	ds_write_b128 v246, v[144:147] offset:17408
	s_waitcnt lgkmcnt(10)
	v_mfma_f32_32x32x16_bf16 v[48:63], v[230:233], v[192:195], v[48:63]
	ds_read_b64_tr_b16 v[8:9], v225 offset:24576
	ds_read_b64_tr_b16 v[10:11], v225 offset:26624
	s_waitcnt vmcnt(2)
	ds_write_b128 v247, v[148:151] offset:16384
	s_waitcnt lgkmcnt(10)
	v_mfma_f32_32x32x16_bf16 v[32:47], v[234:237], v[192:195], v[32:47]
	ds_read_b64_tr_b16 v[12:13], v6 offset:24576
	ds_read_b64_tr_b16 v[14:15], v6 offset:26624
	s_waitcnt vmcnt(1)
	ds_write_b128 v246, v[152:155] offset:26112
	s_waitcnt lgkmcnt(10)
	v_mfma_f32_32x32x16_bf16 v[16:31], v[242:245], v[192:195], v[16:31]
	ds_read_b64_tr_b16 v[226:227], v248 offset:24576
	ds_read_b64_tr_b16 v[228:229], v248 offset:26624
	s_waitcnt vmcnt(0)
	ds_write_b128 v247, v[156:159] offset:24576
	s_waitcnt lgkmcnt(10)
	v_mfma_f32_32x32x16_bf16 v[64:79], v[2:5], v[200:203], v[64:79]
	ds_read_b64_tr_b16 v[230:231], v0 offset:28672
	ds_read_b64_tr_b16 v[232:233], v0 offset:30720
	v_lshlrev_b32_e32 v84, 1, v173
	v_add_u32_e32 v80, 0xffffffa0, v164
	v_ashrrev_i32_e32 v81, 31, v80
	v_lshlrev_b64 v[82:83], 11, v[80:81]
	v_or_b32_e32 v82, v82, v84
	s_waitcnt lgkmcnt(9)
	v_mfma_f32_32x32x16_bf16 v[48:63], v[8:11], v[200:203], v[48:63]
	ds_read_b64_tr_b16 v[234:235], v225 offset:28672
	ds_read_b64_tr_b16 v[236:237], v225 offset:30720
	v_lshl_add_u64 v[86:87], s[86:87], 0, v[82:83]
	v_lshl_add_u64 v[88:89], s[88:89], 0, v[82:83]
	global_load_dwordx4 v[128:131], v[86:87], off
	global_load_dwordx4 v[132:135], v[88:89], off
	s_waitcnt lgkmcnt(8)
	v_mfma_f32_32x32x16_bf16 v[32:47], v[12:15], v[200:203], v[32:47]
	ds_read_b64_tr_b16 v[242:243], v6 offset:28672
	ds_read_b64_tr_b16 v[244:245], v6 offset:30720
	v_subrev_u32_e32 v80, 64, v164
	v_ashrrev_i32_e32 v81, 31, v80
	v_lshlrev_b64 v[82:83], 11, v[80:81]
	v_or_b32_e32 v82, v82, v84
	s_waitcnt lgkmcnt(7)
	v_mfma_f32_32x32x16_bf16 v[16:31], v[226:229], v[200:203], v[16:31]
	ds_read_b64_tr_b16 v[2:3], v248 offset:28672
	ds_read_b64_tr_b16 v[4:5], v248 offset:30720
	v_lshl_add_u64 v[86:87], s[86:87], 0, v[82:83]
	v_lshl_add_u64 v[88:89], s[88:89], 0, v[82:83]
	global_load_dwordx4 v[136:139], v[86:87], off
	global_load_dwordx4 v[140:143], v[88:89], off
	s_waitcnt lgkmcnt(6)
	v_mfma_f32_32x32x16_bf16 v[64:79], v[230:233], v[208:211], v[64:79]
	v_subrev_u32_e32 v80, 32, v164
	v_ashrrev_i32_e32 v81, 31, v80
	v_lshlrev_b64 v[82:83], 11, v[80:81]
	v_or_b32_e32 v82, v82, v84
	s_waitcnt lgkmcnt(4)
	v_mfma_f32_32x32x16_bf16 v[48:63], v[234:237], v[208:211], v[48:63]
	v_lshl_add_u64 v[86:87], s[86:87], 0, v[82:83]
	v_lshl_add_u64 v[88:89], s[88:89], 0, v[82:83]
	global_load_dwordx4 v[144:147], v[86:87], off
	global_load_dwordx4 v[148:151], v[88:89], off
	s_waitcnt lgkmcnt(2)
	v_mfma_f32_32x32x16_bf16 v[32:47], v[242:245], v[208:211], v[32:47]
	v_ashrrev_i32_e32 v165, 31, v164
	v_lshlrev_b64 v[82:83], 11, v[164:165]
	v_or_b32_e32 v82, v82, v84
	v_lshl_add_u64 v[86:87], s[86:87], 0, v[82:83]
	s_waitcnt lgkmcnt(0)
	v_mfma_f32_32x32x16_bf16 v[16:31], v[2:5], v[208:211], v[16:31]
	v_lshl_add_u64 v[88:89], s[88:89], 0, v[82:83]
	global_load_dwordx4 v[152:155], v[86:87], off
	global_load_dwordx4 v[156:159], v[88:89], off
	s_branch .Lattn_stg_done
.Lattn_pair_b6plain:
	s_waitcnt lgkmcnt(6)
	v_mfma_f32_32x32x16_bf16 v[64:79], v[242:245], v[184:187], v[64:79]
	ds_read_b64_tr_b16 v[226:227], v0 offset:20480
	ds_read_b64_tr_b16 v[228:229], v0 offset:22528
	s_waitcnt lgkmcnt(6)
	v_mfma_f32_32x32x16_bf16 v[48:63], v[2:5], v[184:187], v[48:63]
	ds_read_b64_tr_b16 v[230:231], v225 offset:20480
	ds_read_b64_tr_b16 v[232:233], v225 offset:22528
	s_waitcnt lgkmcnt(6)
	v_mfma_f32_32x32x16_bf16 v[32:47], v[8:11], v[184:187], v[32:47]
	ds_read_b64_tr_b16 v[234:235], v6 offset:20480
	ds_read_b64_tr_b16 v[236:237], v6 offset:22528
	s_waitcnt lgkmcnt(6)
	v_mfma_f32_32x32x16_bf16 v[16:31], v[12:15], v[184:187], v[16:31]
	ds_read_b64_tr_b16 v[242:243], v248 offset:20480
	ds_read_b64_tr_b16 v[244:245], v248 offset:22528
	s_waitcnt lgkmcnt(6)
	v_mfma_f32_32x32x16_bf16 v[64:79], v[226:229], v[192:195], v[64:79]
	ds_read_b64_tr_b16 v[2:3], v0 offset:24576
	ds_read_b64_tr_b16 v[4:5], v0 offset:26624
	s_waitcnt lgkmcnt(6)
	v_mfma_f32_32x32x16_bf16 v[48:63], v[230:233], v[192:195], v[48:63]
	ds_read_b64_tr_b16 v[8:9], v225 offset:24576
	ds_read_b64_tr_b16 v[10:11], v225 offset:26624
	s_waitcnt lgkmcnt(6)
	v_mfma_f32_32x32x16_bf16 v[32:47], v[234:237], v[192:195], v[32:47]
	ds_read_b64_tr_b16 v[12:13], v6 offset:24576
	ds_read_b64_tr_b16 v[14:15], v6 offset:26624
	s_waitcnt lgkmcnt(6)
	v_mfma_f32_32x32x16_bf16 v[16:31], v[242:245], v[192:195], v[16:31]
	ds_read_b64_tr_b16 v[226:227], v248 offset:24576
	ds_read_b64_tr_b16 v[228:229], v248 offset:26624
	s_waitcnt lgkmcnt(6)
	v_mfma_f32_32x32x16_bf16 v[64:79], v[2:5], v[200:203], v[64:79]
	ds_read_b64_tr_b16 v[230:231], v0 offset:28672
	ds_read_b64_tr_b16 v[232:233], v0 offset:30720
	s_waitcnt lgkmcnt(6)
	v_mfma_f32_32x32x16_bf16 v[48:63], v[8:11], v[200:203], v[48:63]
	ds_read_b64_tr_b16 v[234:235], v225 offset:28672
	ds_read_b64_tr_b16 v[236:237], v225 offset:30720
	s_waitcnt lgkmcnt(6)
	v_mfma_f32_32x32x16_bf16 v[32:47], v[12:15], v[200:203], v[32:47]
	ds_read_b64_tr_b16 v[242:243], v6 offset:28672
	ds_read_b64_tr_b16 v[244:245], v6 offset:30720
	s_waitcnt lgkmcnt(6)
	v_mfma_f32_32x32x16_bf16 v[16:31], v[226:229], v[200:203], v[16:31]
	ds_read_b64_tr_b16 v[2:3], v248 offset:28672
	ds_read_b64_tr_b16 v[4:5], v248 offset:30720
	s_waitcnt lgkmcnt(6)
	v_mfma_f32_32x32x16_bf16 v[64:79], v[230:233], v[208:211], v[64:79]
	s_waitcnt lgkmcnt(4)
	v_mfma_f32_32x32x16_bf16 v[48:63], v[234:237], v[208:211], v[48:63]
	s_waitcnt lgkmcnt(2)
	v_mfma_f32_32x32x16_bf16 v[32:47], v[242:245], v[208:211], v[32:47]
	s_waitcnt lgkmcnt(0)
	v_mfma_f32_32x32x16_bf16 v[16:31], v[2:5], v[208:211], v[16:31]
	s_branch .LBB0_125

.LBB0_124:
	v_mul_f32_e32 v165, 0xbe38aa3b, v183
	v_fmamk_f32 v2, v96, 0x3e38aa3b, v165
	v_exp_f32_e32 v6, v2
	v_fmamk_f32 v2, v80, 0x3e38aa3b, v165
	v_exp_f32_e32 v188, v2
	v_fmamk_f32 v2, v97, 0x3e38aa3b, v165
	v_exp_f32_e32 v186, v2
	v_fmamk_f32 v2, v81, 0x3e38aa3b, v165
	v_exp_f32_e32 v190, v2
	v_fmamk_f32 v2, v98, 0x3e38aa3b, v165
	v_exp_f32_e32 v187, v2
	v_fmamk_f32 v2, v82, 0x3e38aa3b, v165
	v_exp_f32_e32 v191, v2
	v_fmamk_f32 v2, v99, 0x3e38aa3b, v165
	v_exp_f32_e32 v192, v2
	v_fmamk_f32 v2, v83, 0x3e38aa3b, v165
	v_exp_f32_e32 v193, v2
	v_fmamk_f32 v2, v100, 0x3e38aa3b, v165
	v_exp_f32_e32 v15, v2
	v_fmamk_f32 v2, v84, 0x3e38aa3b, v165
	v_exp_f32_e32 v185, v2
	v_fmamk_f32 v2, v101, 0x3e38aa3b, v165
	v_exp_f32_e32 v14, v2
	v_fmamk_f32 v2, v102, 0x3e38aa3b, v165
	v_exp_f32_e32 v3, v2
	v_fmamk_f32 v2, v103, 0x3e38aa3b, v165
	v_exp_f32_e32 v2, v2
	ds_read_b64_tr_b16 v[10:11], v0 offset:16384
	ds_read_b64_tr_b16 v[12:13], v0 offset:18432
	v_pk_mov_b32 v[8:9], v[14:15], v[14:15] op_sel:[1,0]
	v_pk_mov_b32 v[80:81], v[2:3], v[2:3] op_sel:[1,0]
	v_add_f32_e32 v189, v188, v6
	v_cvt_pk_bf16_f32 v6, v6, v186
	v_cvt_pk_bf16_f32 v7, v187, v192
	v_cvt_pk_bf16_f32 v8, v8, v9
	v_cvt_pk_bf16_f32 v9, v80, v81
	v_fmamk_f32 v4, v104, 0x3e38aa3b, v165
	v_exp_f32_e32 v5, v4
	s_waitcnt lgkmcnt(0)
	v_mfma_f32_32x32x16_bf16 v[64:79], v[10:13], v[6:9], v[64:79]
	v_fmamk_f32 v10, v106, 0x3e38aa3b, v165
	v_fmamk_f32 v4, v105, 0x3e38aa3b, v165
	v_exp_f32_e32 v105, v10
	v_fmamk_f32 v10, v107, 0x3e38aa3b, v165
	v_exp_f32_e32 v104, v10
	v_fmamk_f32 v10, v108, 0x3e38aa3b, v165
	ds_read_b64_tr_b16 v[80:81], v198 offset:16384
	ds_read_b64_tr_b16 v[96:97], v199 offset:16384
	ds_read_b64_tr_b16 v[100:101], v200 offset:16384
	ds_read_b64_tr_b16 v[82:83], v198 offset:18432
	ds_read_b64_tr_b16 v[98:99], v199 offset:18432
	ds_read_b64_tr_b16 v[102:103], v200 offset:18432
	v_exp_f32_e32 v107, v10
	v_fmamk_f32 v10, v109, 0x3e38aa3b, v165
	v_exp_f32_e32 v106, v10
	v_fmamk_f32 v10, v110, 0x3e38aa3b, v165
	v_exp_f32_e32 v4, v4
	v_exp_f32_e32 v109, v10
	v_fmamk_f32 v10, v111, 0x3e38aa3b, v165
	s_waitcnt lgkmcnt(2)
	v_mfma_f32_32x32x16_bf16 v[48:63], v[80:83], v[6:9], v[48:63]
	v_exp_f32_e32 v108, v10
	ds_read_b64_tr_b16 v[80:81], v0 offset:20480
	ds_read_b64_tr_b16 v[82:83], v0 offset:22528
	v_pk_mov_b32 v[10:11], v[4:5], v[4:5] op_sel:[1,0]
	v_pk_mov_b32 v[12:13], v[104:105], v[104:105] op_sel:[1,0]
	v_cvt_pk_bf16_f32 v10, v10, v11
	v_cvt_pk_bf16_f32 v11, v12, v13
	v_pk_mov_b32 v[12:13], v[106:107], v[106:107] op_sel:[1,0]
	s_waitcnt lgkmcnt(3)
	v_mfma_f32_32x32x16_bf16 v[32:47], v[96:99], v[6:9], v[32:47]
	v_pk_mov_b32 v[96:97], v[108:109], v[108:109] op_sel:[1,0]
	v_cvt_pk_bf16_f32 v12, v12, v13
	v_cvt_pk_bf16_f32 v13, v96, v97
	v_add_f32_e32 v195, v191, v187
	v_add_f32_e32 v194, v190, v186
	v_add_f32_e32 v192, v193, v192
	s_waitcnt lgkmcnt(2)
	v_mfma_f32_32x32x16_bf16 v[16:31], v[100:103], v[6:9], v[16:31]
	ds_read_b64_tr_b16 v[6:7], v198 offset:20480
	ds_read_b64_tr_b16 v[96:97], v199 offset:20480
	ds_read_b64_tr_b16 v[100:101], v200 offset:20480
	ds_read_b64_tr_b16 v[8:9], v198 offset:22528
	ds_read_b64_tr_b16 v[98:99], v199 offset:22528
	ds_read_b64_tr_b16 v[102:103], v200 offset:22528
	s_waitcnt lgkmcnt(6)
	v_mfma_f32_32x32x16_bf16 v[64:79], v[80:83], v[10:13], v[64:79]
	v_fmamk_f32 v80, v85, 0x3e38aa3b, v165
	v_exp_f32_e32 v184, v80
	v_fmamk_f32 v80, v86, 0x3e38aa3b, v165
	v_exp_f32_e32 v111, v80
	ds_read_b64_tr_b16 v[80:81], v0 offset:24576
	ds_read_b64_tr_b16 v[82:83], v0 offset:26624
	v_pk_add_f32 v[14:15], v[184:185], v[14:15]
	s_waitcnt lgkmcnt(4)
	v_mfma_f32_32x32x16_bf16 v[48:63], v[6:9], v[10:13], v[48:63]
	v_fmamk_f32 v6, v87, 0x3e38aa3b, v165
	v_exp_f32_e32 v110, v6
	v_fmamk_f32 v6, v88, 0x3e38aa3b, v165
	v_exp_f32_e32 v187, v6
	v_fmamk_f32 v6, v89, 0x3e38aa3b, v165
	v_pk_mov_b32 v[8:9], v[184:185], v[184:185] op_sel:[1,0]
	v_pk_mov_b32 v[84:85], v[110:111], v[110:111] op_sel:[1,0]
	v_exp_f32_e32 v186, v6
	v_cvt_pk_bf16_f32 v6, v188, v190
	v_cvt_pk_bf16_f32 v7, v191, v193
	v_cvt_pk_bf16_f32 v8, v8, v9
	v_cvt_pk_bf16_f32 v9, v84, v85
	s_waitcnt lgkmcnt(3)
	v_mfma_f32_32x32x16_bf16 v[32:47], v[96:99], v[10:13], v[32:47]
	v_add_f32_e64 v2, v110, v2
	v_add_f32_e64 v3, v111, v3
	v_add_f32_e64 v4, v186, v4
	v_add_f32_e64 v5, v187, v5
	s_waitcnt lgkmcnt(2)
	v_mfma_f32_32x32x16_bf16 v[16:31], v[100:103], v[10:13], v[16:31]
	ds_read_b64_tr_b16 v[10:11], v198 offset:24576
	ds_read_b64_tr_b16 v[84:85], v199 offset:24576
	ds_read_b64_tr_b16 v[96:97], v200 offset:24576
	ds_read_b64_tr_b16 v[12:13], v198 offset:26624
	ds_read_b64_tr_b16 v[86:87], v199 offset:26624
	ds_read_b64_tr_b16 v[98:99], v200 offset:26624
	s_waitcnt lgkmcnt(6)
	v_mfma_f32_32x32x16_bf16 v[64:79], v[80:83], v[6:9], v[64:79]
	v_fmamk_f32 v80, v90, 0x3e38aa3b, v165
	v_exp_f32_e32 v101, v80
	v_fmamk_f32 v80, v91, 0x3e38aa3b, v165
	v_exp_f32_e32 v100, v80
	v_fmamk_f32 v80, v92, 0x3e38aa3b, v165
	v_exp_f32_e32 v103, v80
	v_fmamk_f32 v80, v93, 0x3e38aa3b, v165
	s_waitcnt lgkmcnt(2)
	v_mfma_f32_32x32x16_bf16 v[48:63], v[10:13], v[6:9], v[48:63]
	v_fmamk_f32 v10, v94, 0x3e38aa3b, v165
	v_fmac_f32_e32 v165, 0x3e38aa3b, v95
	v_exp_f32_e32 v102, v80
	v_exp_f32_e32 v93, v10
	v_exp_f32_e32 v92, v165
	v_pk_mov_b32 v[10:11], v[186:187], v[186:187] op_sel:[1,0]
	v_pk_mov_b32 v[12:13], v[100:101], v[100:101] op_sel:[1,0]
	v_cvt_pk_bf16_f32 v10, v10, v11
	s_waitcnt lgkmcnt(1)
	v_mfma_f32_32x32x16_bf16 v[32:47], v[84:87], v[6:9], v[32:47]
	v_cvt_pk_bf16_f32 v11, v12, v13
	v_pk_mov_b32 v[12:13], v[102:103], v[102:103] op_sel:[1,0]
	v_pk_mov_b32 v[84:85], v[92:93], v[92:93] op_sel:[1,0]
	v_cvt_pk_bf16_f32 v12, v12, v13
	ds_read_b64_tr_b16 v[80:81], v0 offset:28672
	ds_read_b64_tr_b16 v[82:83], v0 offset:30720
	v_cvt_pk_bf16_f32 v13, v84, v85
	v_pk_add_f32 v[92:93], v[92:93], v[108:109]
	s_waitcnt lgkmcnt(2)
	v_mfma_f32_32x32x16_bf16 v[16:31], v[96:99], v[6:9], v[16:31]
	ds_read_b64_tr_b16 v[6:7], v198 offset:28672
	ds_read_b64_tr_b16 v[84:85], v199 offset:28672
	ds_read_b64_tr_b16 v[88:89], v200 offset:28672
	ds_read_b64_tr_b16 v[8:9], v198 offset:30720
	ds_read_b64_tr_b16 v[86:87], v199 offset:30720
	ds_read_b64_tr_b16 v[90:91], v200 offset:30720
	v_add_f32_e32 v0, 0, v189
	v_add_f32_e32 v0, v194, v0
	v_add_f32_e32 v0, v195, v0
	v_add_f32_e32 v0, v192, v0
	v_add_f32_e32 v0, v15, v0
	v_add_f32_e32 v0, v14, v0
	v_add_f32_e32 v0, v3, v0
	v_add_f32_e32 v0, v2, v0
	v_add_f32_e32 v0, v5, v0
	s_waitcnt lgkmcnt(6)
	v_mfma_f32_32x32x16_bf16 v[64:79], v[80:83], v[10:13], v[64:79]
	v_add_f32_e64 v80, v100, v104
	v_add_f32_e64 v81, v101, v105
	v_add_f32_e32 v0, v4, v0
	v_add_f32_e32 v0, v81, v0
	v_add_f32_e64 v82, v102, v106
	v_add_f32_e64 v83, v103, v107
	v_add_f32_e32 v0, v80, v0
	v_add_f32_e32 v0, v83, v0
	v_add_f32_e32 v0, v82, v0
	s_waitcnt lgkmcnt(2)
	v_mfma_f32_32x32x16_bf16 v[48:63], v[6:9], v[10:13], v[48:63]
	v_add_f32_e32 v0, v93, v0
	v_add_f32_e32 v0, v92, v0
	v_add_f32_e32 v182, v0, v182
	s_waitcnt lgkmcnt(1)
	v_mfma_f32_32x32x16_bf16 v[32:47], v[84:87], v[10:13], v[32:47]
	s_waitcnt lgkmcnt(0)
	v_mfma_f32_32x32x16_bf16 v[16:31], v[88:91], v[10:13], v[16:31]
.LBB0_125:
	s_cmp_ge_u32 s12, s10
	s_cbranch_scc1 .Lattn_stg_ld
	s_and_b32 s14, s13, 1
	s_mul_i32 s15, s14, 0x8800
	s_mul_i32 s14, s14, 0x9000
	v_add3_u32 v0, v176, s15, v174
	v_add3_u32 v2, v177, s14, v175
	s_waitcnt vmcnt(7)
	ds_write_b128 v0, v[128:131]
	s_waitcnt vmcnt(6)
	ds_write_b128 v2, v[132:135]
	s_waitcnt vmcnt(5)
	ds_write_b128 v0, v[136:139] offset:8704
	s_waitcnt vmcnt(4)
	ds_write_b128 v2, v[140:143] offset:8192
	s_waitcnt vmcnt(3)
	ds_write_b128 v0, v[144:147] offset:17408
	s_waitcnt vmcnt(2)
	ds_write_b128 v2, v[148:151] offset:16384
	s_waitcnt vmcnt(1)
	ds_write_b128 v0, v[152:155] offset:26112
	s_waitcnt vmcnt(0)
	ds_write_b128 v2, v[156:159] offset:24576

.Lattn_stg_done:
	s_add_i32 s2, s2, 2
	s_cmp_eq_u32 s12, s10
	v_add_u32_e32 v164, 0x80, v164
	s_waitcnt lgkmcnt(0)
	s_barrier
	s_cbranch_scc0 .LBB0_112
	s_setprio 0
	v_and_b32_e32 v2, 64, v220
	v_xor_b32_e32 v0, 32, v220
	v_add_u32_e32 v2, 64, v2
	v_cmp_lt_i32_e32 vcc, v0, v2
	s_lshl_b32 s2, s8, 14
	s_add_i32 s2, s2, 0
	v_cndmask_b32_e32 v0, v220, v0, vcc
	s_waitcnt vmcnt(1)
	v_lshlrev_b32_e32 v121, 2, v0
	ds_bpermute_b32 v0, v121, v182
	s_cmp_eq_u32 s11, 1
	v_lshl_add_u32 v2, v170, 2, s2
	s_waitcnt lgkmcnt(0)
	v_add_f32_e32 v0, v182, v0
	s_cbranch_scc0 .LBB0_128
	v_div_scale_f32 v3, s[2:3], v0, v0, v166
	v_rcp_f32_e32 v4, v3
	v_div_scale_f32 v5, vcc, v166, v0, v166
	v_fma_f32 v6, -v3, v4, 1.0
	v_fmac_f32_e32 v4, v6, v4
	v_mul_f32_e32 v6, v5, v4
	v_fma_f32 v7, -v3, v6, v5
	v_fmac_f32_e32 v6, v7, v4
	v_fma_f32 v3, -v3, v6, v5
	v_div_fmas_f32 v3, v3, v4, v6
	v_div_fixup_f32 v3, v3, v0, v166
	v_mul_f32_e32 v4, v64, v3
	v_mul_f32_e32 v5, v65, v3
	ds_write2st64_b32 v2, v4, v5 offset1:1
	v_mul_f32_e32 v4, v66, v3
	v_mul_f32_e32 v5, v67, v3
	ds_write2st64_b32 v2, v4, v5 offset0:2 offset1:3
	v_mul_f32_e32 v4, v68, v3
	v_mul_f32_e32 v5, v69, v3
	ds_write2st64_b32 v2, v4, v5 offset0:4 offset1:5
	v_mul_f32_e32 v4, v70, v3
	v_mul_f32_e32 v5, v71, v3
	ds_write2st64_b32 v2, v4, v5 offset0:6 offset1:7
	v_mul_f32_e32 v4, v72, v3
	v_mul_f32_e32 v5, v73, v3
	ds_write2st64_b32 v2, v4, v5 offset0:8 offset1:9
	v_mul_f32_e32 v4, v74, v3
	v_mul_f32_e32 v5, v75, v3
	ds_write2st64_b32 v2, v4, v5 offset0:10 offset1:11
	v_mul_f32_e32 v4, v76, v3
	v_mul_f32_e32 v5, v77, v3
	ds_write2st64_b32 v2, v4, v5 offset0:12 offset1:13
	v_mul_f32_e32 v4, v78, v3
	v_mul_f32_e32 v5, v79, v3
	ds_write2st64_b32 v2, v4, v5 offset0:14 offset1:15
	v_mul_f32_e32 v4, v48, v3
	v_mul_f32_e32 v5, v49, v3
	ds_write2st64_b32 v2, v4, v5 offset0:16 offset1:17
	v_mul_f32_e32 v4, v50, v3
	v_mul_f32_e32 v5, v51, v3
	ds_write2st64_b32 v2, v4, v5 offset0:18 offset1:19
	v_mul_f32_e32 v4, v52, v3
	v_mul_f32_e32 v5, v53, v3
	ds_write2st64_b32 v2, v4, v5 offset0:20 offset1:21
	v_mul_f32_e32 v4, v54, v3
	v_mul_f32_e32 v5, v55, v3
	ds_write2st64_b32 v2, v4, v5 offset0:22 offset1:23
	v_mul_f32_e32 v4, v56, v3
	v_mul_f32_e32 v5, v57, v3
	ds_write2st64_b32 v2, v4, v5 offset0:24 offset1:25
	v_mul_f32_e32 v4, v58, v3
	v_mul_f32_e32 v5, v59, v3
	ds_write2st64_b32 v2, v4, v5 offset0:26 offset1:27
	v_mul_f32_e32 v4, v60, v3
	v_mul_f32_e32 v5, v61, v3
	ds_write2st64_b32 v2, v4, v5 offset0:28 offset1:29
	v_mul_f32_e32 v4, v62, v3
	v_mul_f32_e32 v5, v63, v3
	ds_write2st64_b32 v2, v4, v5 offset0:30 offset1:31
	v_mul_f32_e32 v4, v32, v3
	v_mul_f32_e32 v5, v33, v3
	ds_write2st64_b32 v2, v4, v5 offset0:32 offset1:33
	v_mul_f32_e32 v4, v34, v3
	v_mul_f32_e32 v5, v35, v3
	ds_write2st64_b32 v2, v4, v5 offset0:34 offset1:35
	v_mul_f32_e32 v4, v36, v3
	v_mul_f32_e32 v5, v37, v3
	ds_write2st64_b32 v2, v4, v5 offset0:36 offset1:37
	v_mul_f32_e32 v4, v38, v3
	v_mul_f32_e32 v5, v39, v3
	ds_write2st64_b32 v2, v4, v5 offset0:38 offset1:39
	v_mul_f32_e32 v4, v40, v3
	v_mul_f32_e32 v5, v41, v3
	ds_write2st64_b32 v2, v4, v5 offset0:40 offset1:41
	v_mul_f32_e32 v4, v42, v3
	v_mul_f32_e32 v5, v43, v3
	ds_write2st64_b32 v2, v4, v5 offset0:42 offset1:43
	v_mul_f32_e32 v4, v44, v3
	v_mul_f32_e32 v5, v45, v3
	ds_write2st64_b32 v2, v4, v5 offset0:44 offset1:45
	v_mul_f32_e32 v4, v46, v3
	v_mul_f32_e32 v5, v47, v3
	ds_write2st64_b32 v2, v4, v5 offset0:46 offset1:47
	v_mul_f32_e32 v4, v16, v3
	v_mul_f32_e32 v5, v17, v3
	ds_write2st64_b32 v2, v4, v5 offset0:48 offset1:49
	v_mul_f32_e32 v4, v18, v3
	v_mul_f32_e32 v5, v19, v3
	ds_write2st64_b32 v2, v4, v5 offset0:50 offset1:51
	v_mul_f32_e32 v4, v20, v3
	v_mul_f32_e32 v5, v21, v3
	ds_write2st64_b32 v2, v4, v5 offset0:52 offset1:53
	v_mul_f32_e32 v4, v22, v3
	v_mul_f32_e32 v5, v23, v3
	ds_write2st64_b32 v2, v4, v5 offset0:54 offset1:55
	v_mul_f32_e32 v4, v24, v3
	v_mul_f32_e32 v5, v25, v3
	ds_write2st64_b32 v2, v4, v5 offset0:56 offset1:57
	v_mul_f32_e32 v4, v26, v3
	v_mul_f32_e32 v5, v27, v3
	ds_write2st64_b32 v2, v4, v5 offset0:58 offset1:59
	v_mul_f32_e32 v4, v28, v3
	v_mul_f32_e32 v5, v29, v3
	ds_write2st64_b32 v2, v4, v5 offset0:60 offset1:61
	v_mul_f32_e32 v4, v30, v3
	v_mul_f32_e32 v3, v31, v3
	ds_write2st64_b32 v2, v4, v3 offset0:62 offset1:63
